# v24: first K-loop iteration peeled in MLP-in and in-proj, accumulators start from inline 0 (no 128 v_mov per unit)
# baseline (speedup 1.0000x reference)
.LBB0_100:
	s_ashr_i32 s11, s10, 31
	s_lshl_b64 s[18:19], s[10:11], 20
	v_readlane_b32 s36, v255, 9
	v_readlane_b32 s37, v255, 10
	s_add_u32 s36, s36, s18
	s_addc_u32 s37, s37, s19
	s_and_b64 s[18:19], s[38:39], exec
	s_cselect_b32 s11, s37, s17
	s_cselect_b32 s44, s36, s16
	s_ashr_i32 s9, s8, 31
	s_lshl_b64 s[18:19], s[8:9], 20
	s_add_u32 s40, s20, s18
	s_addc_u32 s41, s21, s19
	s_and_b64 s[18:19], s[38:39], exec
	s_cselect_b32 s9, s41, s15
	s_cselect_b32 s45, s40, s14
	s_add_u32 s46, s14, 0x8000
	s_addc_u32 s47, s15, 0
	s_add_u32 s14, s16, 0x80080
	s_addc_u32 s15, s17, 0
	s_mov_b32 s48, -2
	s_add_u32 s16, s14, 0xfff80080
	s_addc_u32 s17, s15, -1
	s_add_i32 s49, 0, 0x10000
	s_cmp_eq_u32 s48, 28
	s_cselect_b32 s19, s11, s17
	s_cselect_b32 s18, s44, s16
	v_add_u32_e32 v144, s49, v147
	s_cselect_b32 s17, s9, s47
	s_cselect_b32 s16, s45, s46
	s_add_i32 s52, 0, 0x14000
	ds_read_b128 v[140:143], v144
	ds_read_b128 v[150:153], v144 offset:1024
	ds_read_b128 v[154:157], v144 offset:2048
	ds_read_b128 v[158:161], v144 offset:3072
	v_add_u32_e32 v144, s52, v147
	ds_read_b128 v[162:165], v144
	ds_read_b128 v[166:169], v144 offset:1024
	ds_read_b128 v[170:173], v144 offset:2048
	ds_read_b128 v[174:177], v144 offset:3072
	v_lshl_add_u64 v[144:145], s[14:15], 0, v[138:139]
	s_add_i32 m0, s23, 0xc000
	ds_read_b128 v[178:181], v149
	ds_read_b128 v[182:185], v149 offset:1024
	ds_read_b128 v[186:189], v149 offset:2048
	ds_read_b128 v[190:193], v149 offset:3072
	ds_read_b128 v[194:197], v149 offset:4096
	ds_read_b128 v[198:201], v149 offset:5120
	ds_read_b128 v[202:205], v149 offset:6144
	ds_read_b128 v[206:209], v149 offset:7168
	global_load_lds_dwordx4 v[144:145], off
	v_lshl_add_u64 v[144:145], s[14:15], 0, v[136:137]
	s_add_i32 m0, s23, 0xe000
	s_nop 0
	global_load_lds_dwordx4 v[144:145], off
	s_cmp_eq_u32 s98, 0
	s_cbranch_scc1 .Lpw_mi1_n_pmi
	s_waitcnt vmcnt(24)
	s_branch .Lpw_mi1_d_pmi

.Lpw_mi1_d_pmi:
	s_waitcnt lgkmcnt(0)
	s_barrier
	s_setprio 1
	s_waitcnt lgkmcnt(0)
	v_mfma_f32_16x16x32_bf16 v[124:127], v[140:143], v[178:181], 0
	v_mfma_f32_16x16x32_bf16 v[120:123], v[154:157], v[178:181], 0
	v_mfma_f32_16x16x32_bf16 v[108:111], v[140:143], v[186:189], 0
	v_mfma_f32_16x16x32_bf16 v[104:107], v[154:157], v[186:189], 0
	v_mfma_f32_16x16x32_bf16 v[92:95], v[140:143], v[194:197], 0
	v_mfma_f32_16x16x32_bf16 v[88:91], v[154:157], v[194:197], 0
	v_mfma_f32_16x16x32_bf16 v[76:79], v[140:143], v[202:205], 0
	v_mfma_f32_16x16x32_bf16 v[72:75], v[154:157], v[202:205], 0
	v_mfma_f32_16x16x32_bf16 v[124:127], v[150:153], v[182:185], v[124:127]
	v_mfma_f32_16x16x32_bf16 v[120:123], v[158:161], v[182:185], v[120:123]
	v_mfma_f32_16x16x32_bf16 v[108:111], v[150:153], v[190:193], v[108:111]
	v_mfma_f32_16x16x32_bf16 v[104:107], v[158:161], v[190:193], v[104:107]
	v_mfma_f32_16x16x32_bf16 v[92:95], v[150:153], v[198:201], v[92:95]
	v_mfma_f32_16x16x32_bf16 v[88:91], v[158:161], v[198:201], v[88:91]
	v_mfma_f32_16x16x32_bf16 v[76:79], v[150:153], v[206:209], v[76:79]
	v_mfma_f32_16x16x32_bf16 v[72:75], v[158:161], v[206:209], v[72:75]
	s_setprio 0
	s_setprio 1
	v_mfma_f32_16x16x32_bf16 v[116:119], v[162:165], v[178:181], 0
	v_mfma_f32_16x16x32_bf16 v[112:115], v[170:173], v[178:181], 0
	v_mfma_f32_16x16x32_bf16 v[100:103], v[162:165], v[186:189], 0
	v_mfma_f32_16x16x32_bf16 v[96:99], v[170:173], v[186:189], 0
	v_mfma_f32_16x16x32_bf16 v[84:87], v[162:165], v[194:197], 0
	v_mfma_f32_16x16x32_bf16 v[80:83], v[170:173], v[194:197], 0
	v_mfma_f32_16x16x32_bf16 v[68:71], v[162:165], v[202:205], 0
	v_mfma_f32_16x16x32_bf16 v[64:67], v[170:173], v[202:205], 0
	v_mfma_f32_16x16x32_bf16 v[116:119], v[166:169], v[182:185], v[116:119]
	v_mfma_f32_16x16x32_bf16 v[112:115], v[174:177], v[182:185], v[112:115]
	v_mfma_f32_16x16x32_bf16 v[100:103], v[166:169], v[190:193], v[100:103]
	v_mfma_f32_16x16x32_bf16 v[96:99], v[174:177], v[190:193], v[96:99]
	v_mfma_f32_16x16x32_bf16 v[84:87], v[166:169], v[198:201], v[84:87]
	v_mfma_f32_16x16x32_bf16 v[80:83], v[174:177], v[198:201], v[80:83]
	v_mfma_f32_16x16x32_bf16 v[68:71], v[166:169], v[206:209], v[68:71]
	v_mfma_f32_16x16x32_bf16 v[64:67], v[174:177], v[206:209], v[64:67]
	s_setprio 0
	s_barrier
	s_add_i32 s49, s49, s22
	v_lshl_add_u64 v[144:145], s[16:17], 0, v[134:135]
	s_mov_b32 m0, s49
	ds_read_b128 v[178:181], v149 offset:16384
	ds_read_b128 v[182:185], v149 offset:17408
	ds_read_b128 v[186:189], v149 offset:18432
	ds_read_b128 v[190:193], v149 offset:19456
	ds_read_b128 v[194:197], v149 offset:20480
	ds_read_b128 v[198:201], v149 offset:21504
	ds_read_b128 v[202:205], v149 offset:22528
	ds_read_b128 v[206:209], v149 offset:23552
	global_load_lds_dwordx4 v[144:145], off
	s_add_i32 m0, s49, 0x2000
	s_add_u32 s50, s16, 0x80000
	v_lshl_add_u64 v[144:145], s[16:17], 0, v[130:131]
	s_addc_u32 s51, s17, 0
	s_add_i32 s49, s52, s22
	global_load_lds_dwordx4 v[144:145], off
	v_lshl_add_u64 v[144:145], s[50:51], 0, v[134:135]
	s_mov_b32 m0, s49
	v_lshl_add_u64 v[210:211], s[18:19], 0, v[132:133]
	global_load_lds_dwordx4 v[144:145], off
	v_lshl_add_u64 v[144:145], s[50:51], 0, v[130:131]
	s_add_i32 m0, s49, 0x2000
	s_nop 0
	global_load_lds_dwordx4 v[144:145], off
	v_lshl_add_u64 v[144:145], s[18:19], 0, v[128:129]
	s_mov_b32 m0, s23
	s_nop 0
	global_load_lds_dwordx4 v[144:145], off
	s_mov_b32 m0, s24
	s_nop 0
	global_load_lds_dwordx4 v[210:211], off
	s_cmp_eq_u32 s98, 0
	s_cbranch_scc1 .Lpw_mi2_n_pmi
	s_waitcnt vmcnt(24)
	s_mov_b32 s98, 0
	s_branch .Lpw_mi2_d_pmi

.Lpw_mi2_d_pmi:
	s_waitcnt lgkmcnt(0)
	s_barrier
	s_setprio 1
	s_waitcnt lgkmcnt(0)
	v_mfma_f32_16x16x32_bf16 v[60:63], v[140:143], v[178:181], 0
	v_mfma_f32_16x16x32_bf16 v[56:59], v[154:157], v[178:181], 0
	v_mfma_f32_16x16x32_bf16 v[44:47], v[140:143], v[186:189], 0
	v_mfma_f32_16x16x32_bf16 v[40:43], v[154:157], v[186:189], 0
	v_mfma_f32_16x16x32_bf16 v[28:31], v[140:143], v[194:197], 0
	v_mfma_f32_16x16x32_bf16 v[24:27], v[154:157], v[194:197], 0
	v_mfma_f32_16x16x32_bf16 v[12:15], v[140:143], v[202:205], 0
	v_mfma_f32_16x16x32_bf16 v[8:11], v[154:157], v[202:205], 0
	v_mfma_f32_16x16x32_bf16 v[60:63], v[150:153], v[182:185], v[60:63]
	v_mfma_f32_16x16x32_bf16 v[56:59], v[158:161], v[182:185], v[56:59]
	v_mfma_f32_16x16x32_bf16 v[44:47], v[150:153], v[190:193], v[44:47]
	v_mfma_f32_16x16x32_bf16 v[40:43], v[158:161], v[190:193], v[40:43]
	v_mfma_f32_16x16x32_bf16 v[28:31], v[150:153], v[198:201], v[28:31]
	v_mfma_f32_16x16x32_bf16 v[24:27], v[158:161], v[198:201], v[24:27]
	v_mfma_f32_16x16x32_bf16 v[12:15], v[150:153], v[206:209], v[12:15]
	v_mfma_f32_16x16x32_bf16 v[8:11], v[158:161], v[206:209], v[8:11]
	s_setprio 0
	s_setprio 1
	v_mfma_f32_16x16x32_bf16 v[52:55], v[162:165], v[178:181], 0
	v_mfma_f32_16x16x32_bf16 v[48:51], v[170:173], v[178:181], 0
	v_mfma_f32_16x16x32_bf16 v[36:39], v[162:165], v[186:189], 0
	v_mfma_f32_16x16x32_bf16 v[32:35], v[170:173], v[186:189], 0
	v_mfma_f32_16x16x32_bf16 v[20:23], v[162:165], v[194:197], 0
	v_mfma_f32_16x16x32_bf16 v[16:19], v[170:173], v[194:197], 0
	v_mfma_f32_16x16x32_bf16 v[4:7], v[162:165], v[202:205], 0
	v_mfma_f32_16x16x32_bf16 v[0:3], v[170:173], v[202:205], 0
	v_mfma_f32_16x16x32_bf16 v[52:55], v[166:169], v[182:185], v[52:55]
	v_mfma_f32_16x16x32_bf16 v[48:51], v[174:177], v[182:185], v[48:51]
	v_mfma_f32_16x16x32_bf16 v[36:39], v[166:169], v[190:193], v[36:39]
	v_mfma_f32_16x16x32_bf16 v[32:35], v[174:177], v[190:193], v[32:35]
	v_mfma_f32_16x16x32_bf16 v[20:23], v[166:169], v[198:201], v[20:23]
	v_mfma_f32_16x16x32_bf16 v[16:19], v[174:177], v[198:201], v[16:19]
	v_mfma_f32_16x16x32_bf16 v[4:7], v[166:169], v[206:209], v[4:7]
	v_mfma_f32_16x16x32_bf16 v[0:3], v[174:177], v[206:209], v[0:3]
	s_setprio 0
	s_barrier
	s_add_i32 s49, 0, 0x18000
	s_add_i32 s50, 0, 0x1c000
	v_add_u32_e32 v158, s49, v147
	v_add_u32_e32 v174, s50, v147
	ds_read_b128 v[140:143], v158
	ds_read_b128 v[150:153], v158 offset:1024
	ds_read_b128 v[154:157], v158 offset:2048
	ds_read_b128 v[158:161], v158 offset:3072
	ds_read_b128 v[162:165], v174
	ds_read_b128 v[166:169], v174 offset:1024
	ds_read_b128 v[170:173], v174 offset:2048
	ds_read_b128 v[174:177], v174 offset:3072
	s_add_u32 s18, s18, 0x80000
	s_addc_u32 s19, s19, 0
	s_mov_b32 m0, s25
	v_lshl_add_u64 v[212:213], s[18:19], 0, v[128:129]
	ds_read_b128 v[178:181], v149 offset:32768
	ds_read_b128 v[182:185], v149 offset:33792
	ds_read_b128 v[186:189], v149 offset:34816
	ds_read_b128 v[190:193], v149 offset:35840
	ds_read_b128 v[194:197], v149 offset:36864
	ds_read_b128 v[198:201], v149 offset:37888
	ds_read_b128 v[202:205], v149 offset:38912
	ds_read_b128 v[206:209], v149 offset:39936
	global_load_lds_dwordx4 v[212:213], off
	v_lshl_add_u64 v[212:213], s[18:19], 0, v[132:133]
	s_mov_b32 m0, s26
	s_nop 0
	global_load_lds_dwordx4 v[212:213], off
	s_waitcnt vmcnt(8)
	s_waitcnt lgkmcnt(0)
	s_barrier
	s_setprio 1
	s_waitcnt lgkmcnt(0)
	v_mfma_f32_16x16x32_bf16 v[124:127], v[140:143], v[178:181], v[124:127]
	v_mfma_f32_16x16x32_bf16 v[120:123], v[154:157], v[178:181], v[120:123]
	v_mfma_f32_16x16x32_bf16 v[108:111], v[140:143], v[186:189], v[108:111]
	v_mfma_f32_16x16x32_bf16 v[104:107], v[154:157], v[186:189], v[104:107]
	v_mfma_f32_16x16x32_bf16 v[92:95], v[140:143], v[194:197], v[92:95]
	v_mfma_f32_16x16x32_bf16 v[88:91], v[154:157], v[194:197], v[88:91]
	v_mfma_f32_16x16x32_bf16 v[76:79], v[140:143], v[202:205], v[76:79]
	v_mfma_f32_16x16x32_bf16 v[72:75], v[154:157], v[202:205], v[72:75]
	v_mfma_f32_16x16x32_bf16 v[124:127], v[150:153], v[182:185], v[124:127]
	v_mfma_f32_16x16x32_bf16 v[120:123], v[158:161], v[182:185], v[120:123]
	v_mfma_f32_16x16x32_bf16 v[108:111], v[150:153], v[190:193], v[108:111]
	v_mfma_f32_16x16x32_bf16 v[104:107], v[158:161], v[190:193], v[104:107]
	v_mfma_f32_16x16x32_bf16 v[92:95], v[150:153], v[198:201], v[92:95]
	v_mfma_f32_16x16x32_bf16 v[88:91], v[158:161], v[198:201], v[88:91]
	v_mfma_f32_16x16x32_bf16 v[76:79], v[150:153], v[206:209], v[76:79]
	v_mfma_f32_16x16x32_bf16 v[72:75], v[158:161], v[206:209], v[72:75]
	s_setprio 0
	s_setprio 1
	v_mfma_f32_16x16x32_bf16 v[116:119], v[162:165], v[178:181], v[116:119]
	v_mfma_f32_16x16x32_bf16 v[112:115], v[170:173], v[178:181], v[112:115]
	v_mfma_f32_16x16x32_bf16 v[100:103], v[162:165], v[186:189], v[100:103]
	v_mfma_f32_16x16x32_bf16 v[96:99], v[170:173], v[186:189], v[96:99]
	v_mfma_f32_16x16x32_bf16 v[84:87], v[162:165], v[194:197], v[84:87]
	v_mfma_f32_16x16x32_bf16 v[80:83], v[170:173], v[194:197], v[80:83]
	v_mfma_f32_16x16x32_bf16 v[68:71], v[162:165], v[202:205], v[68:71]
	v_mfma_f32_16x16x32_bf16 v[64:67], v[170:173], v[202:205], v[64:67]
	v_mfma_f32_16x16x32_bf16 v[116:119], v[166:169], v[182:185], v[116:119]
	v_mfma_f32_16x16x32_bf16 v[112:115], v[174:177], v[182:185], v[112:115]
	v_mfma_f32_16x16x32_bf16 v[100:103], v[166:169], v[190:193], v[100:103]
	v_mfma_f32_16x16x32_bf16 v[96:99], v[174:177], v[190:193], v[96:99]
	v_mfma_f32_16x16x32_bf16 v[84:87], v[166:169], v[198:201], v[84:87]
	v_mfma_f32_16x16x32_bf16 v[80:83], v[174:177], v[198:201], v[80:83]
	v_mfma_f32_16x16x32_bf16 v[68:71], v[166:169], v[206:209], v[68:71]
	v_mfma_f32_16x16x32_bf16 v[64:67], v[174:177], v[206:209], v[64:67]
	s_setprio 0
	s_barrier
	s_add_u32 s18, s16, 0x4000
	s_addc_u32 s19, s17, 0
	s_add_i32 s49, s49, s22
	v_lshl_add_u64 v[212:213], s[18:19], 0, v[134:135]
	s_mov_b32 m0, s49
	ds_read_b128 v[178:181], v149 offset:49152
	ds_read_b128 v[182:185], v149 offset:50176
	ds_read_b128 v[186:189], v149 offset:51200
	ds_read_b128 v[190:193], v149 offset:52224
	ds_read_b128 v[194:197], v149 offset:53248
	ds_read_b128 v[198:201], v149 offset:54272
	ds_read_b128 v[202:205], v149 offset:55296
	ds_read_b128 v[206:209], v149 offset:56320
	global_load_lds_dwordx4 v[212:213], off
	s_add_i32 m0, s49, 0x2000
	s_add_u32 s16, s16, 0x84000
	v_lshl_add_u64 v[212:213], s[18:19], 0, v[130:131]
	s_addc_u32 s17, s17, 0
	s_add_i32 s18, s50, s22
	global_load_lds_dwordx4 v[212:213], off
	v_lshl_add_u64 v[212:213], s[16:17], 0, v[134:135]
	s_mov_b32 m0, s18
	v_lshl_add_u64 v[144:145], v[144:145], 0, s[34:35]
	global_load_lds_dwordx4 v[212:213], off
	v_lshl_add_u64 v[212:213], s[16:17], 0, v[130:131]
	s_add_i32 m0, s18, 0x2000
	s_nop 0
	global_load_lds_dwordx4 v[212:213], off
	s_mov_b32 m0, s28
	s_nop 0
	global_load_lds_dwordx4 v[144:145], off
	v_lshl_add_u64 v[144:145], v[210:211], 0, s[34:35]
	s_mov_b32 m0, s29
	s_nop 0
	global_load_lds_dwordx4 v[144:145], off
	s_waitcnt vmcnt(8)
	s_waitcnt lgkmcnt(0)
	s_barrier
	s_setprio 1
	s_waitcnt lgkmcnt(0)
	v_mfma_f32_16x16x32_bf16 v[60:63], v[140:143], v[178:181], v[60:63]
	v_mfma_f32_16x16x32_bf16 v[56:59], v[154:157], v[178:181], v[56:59]
	v_mfma_f32_16x16x32_bf16 v[44:47], v[140:143], v[186:189], v[44:47]
	v_mfma_f32_16x16x32_bf16 v[40:43], v[154:157], v[186:189], v[40:43]
	v_mfma_f32_16x16x32_bf16 v[28:31], v[140:143], v[194:197], v[28:31]
	v_mfma_f32_16x16x32_bf16 v[24:27], v[154:157], v[194:197], v[24:27]
	v_mfma_f32_16x16x32_bf16 v[12:15], v[140:143], v[202:205], v[12:15]
	v_mfma_f32_16x16x32_bf16 v[8:11], v[154:157], v[202:205], v[8:11]
	v_mfma_f32_16x16x32_bf16 v[60:63], v[150:153], v[182:185], v[60:63]
	v_mfma_f32_16x16x32_bf16 v[56:59], v[158:161], v[182:185], v[56:59]
	v_mfma_f32_16x16x32_bf16 v[44:47], v[150:153], v[190:193], v[44:47]
	v_mfma_f32_16x16x32_bf16 v[40:43], v[158:161], v[190:193], v[40:43]
	v_mfma_f32_16x16x32_bf16 v[28:31], v[150:153], v[198:201], v[28:31]
	v_mfma_f32_16x16x32_bf16 v[24:27], v[158:161], v[198:201], v[24:27]
	v_mfma_f32_16x16x32_bf16 v[12:15], v[150:153], v[206:209], v[12:15]
	v_mfma_f32_16x16x32_bf16 v[8:11], v[158:161], v[206:209], v[8:11]
	s_setprio 0
	s_setprio 1
	v_mfma_f32_16x16x32_bf16 v[52:55], v[162:165], v[178:181], v[52:55]
	v_mfma_f32_16x16x32_bf16 v[48:51], v[170:173], v[178:181], v[48:51]
	v_mfma_f32_16x16x32_bf16 v[36:39], v[162:165], v[186:189], v[36:39]
	v_mfma_f32_16x16x32_bf16 v[32:35], v[170:173], v[186:189], v[32:35]
	v_mfma_f32_16x16x32_bf16 v[20:23], v[162:165], v[194:197], v[20:23]
	v_mfma_f32_16x16x32_bf16 v[16:19], v[170:173], v[194:197], v[16:19]
	v_mfma_f32_16x16x32_bf16 v[4:7], v[162:165], v[202:205], v[4:7]
	v_mfma_f32_16x16x32_bf16 v[0:3], v[170:173], v[202:205], v[0:3]
	v_mfma_f32_16x16x32_bf16 v[52:55], v[166:169], v[182:185], v[52:55]
	v_mfma_f32_16x16x32_bf16 v[48:51], v[174:177], v[182:185], v[48:51]
	v_mfma_f32_16x16x32_bf16 v[36:39], v[166:169], v[190:193], v[36:39]
	v_mfma_f32_16x16x32_bf16 v[32:35], v[174:177], v[190:193], v[32:35]
	v_mfma_f32_16x16x32_bf16 v[20:23], v[166:169], v[198:201], v[20:23]
	v_mfma_f32_16x16x32_bf16 v[16:19], v[174:177], v[198:201], v[16:19]
	v_mfma_f32_16x16x32_bf16 v[4:7], v[166:169], v[206:209], v[4:7]
	v_mfma_f32_16x16x32_bf16 v[0:3], v[174:177], v[206:209], v[0:3]
	s_setprio 0
	s_barrier
	s_add_i32 s48, s48, 2
	s_add_u32 s46, s46, 0x8000
	s_addc_u32 s47, s47, 0
	s_add_u32 s14, s14, 0x100
	s_addc_u32 s15, s15, 0
	s_cmp_gt_u32 s48, 29
	s_cbranch_scc0 .LBB0_101
	s_branch .Lpz_mi_exit

.Lpz_mi_exit:
	s_and_b64 vcc, exec, s[6:7]
	s_cbranch_vccz .LBB0_104
	s_barrier

.LBB0_549:
	s_ashr_i32 s11, s10, 31
	s_lshl_b64 s[18:19], s[10:11], 20
	v_readlane_b32 s36, v255, 9
	v_readlane_b32 s37, v255, 10
	s_add_u32 s36, s36, s18
	s_addc_u32 s37, s37, s19
	s_and_b64 s[18:19], s[38:39], exec
	s_cselect_b32 s11, s37, s17
	s_cselect_b32 s44, s36, s16
	s_ashr_i32 s9, s8, 31
	s_lshl_b64 s[18:19], s[8:9], 20
	s_add_u32 s40, s21, s18
	s_addc_u32 s41, s22, s19
	s_and_b64 s[18:19], s[38:39], exec
	s_cselect_b32 s9, s41, s15
	s_cselect_b32 s45, s40, s14
	s_add_u32 s46, s14, 0x8000
	s_addc_u32 s47, s15, 0
	s_add_u32 s14, s16, 0x80080
	s_addc_u32 s15, s17, 0
	s_mov_b32 s48, -2
	s_add_u32 s16, s14, 0xfff80080
	s_addc_u32 s17, s15, -1
	s_add_i32 s49, 0, 0x10000
	s_cmp_eq_u32 s48, 28
	s_cselect_b32 s19, s11, s17
	s_cselect_b32 s18, s44, s16
	s_cselect_b32 s17, s9, s47
	s_cselect_b32 s16, s45, s46
	s_add_i32 s52, 0, 0x14000
	v_add_u32_e32 v156, s49, v145
	v_add_u32_e32 v172, s52, v145
	ds_read_b128 v[140:143], v156
	ds_read_b128 v[148:151], v156 offset:1024
	ds_read_b128 v[152:155], v156 offset:2048
	ds_read_b128 v[156:159], v156 offset:3072
	ds_read_b128 v[160:163], v172
	ds_read_b128 v[164:167], v172 offset:1024
	ds_read_b128 v[168:171], v172 offset:2048
	ds_read_b128 v[172:175], v172 offset:3072
	v_lshl_add_u64 v[208:209], s[14:15], 0, v[138:139]
	s_add_i32 m0, s24, 0xc000
	ds_read_b128 v[176:179], v147
	ds_read_b128 v[180:183], v147 offset:1024
	ds_read_b128 v[184:187], v147 offset:2048
	ds_read_b128 v[188:191], v147 offset:3072
	ds_read_b128 v[192:195], v147 offset:4096
	ds_read_b128 v[196:199], v147 offset:5120
	ds_read_b128 v[200:203], v147 offset:6144
	ds_read_b128 v[204:207], v147 offset:7168
	global_load_lds_dwordx4 v[208:209], off
	v_lshl_add_u64 v[208:209], s[14:15], 0, v[136:137]
	s_add_i32 m0, s24, 0xe000
	s_nop 0
	global_load_lds_dwordx4 v[208:209], off
	s_cmp_eq_u32 s98, 0
	s_cbranch_scc1 .Lpw_ip1_n_pip
	s_waitcnt vmcnt(24)
	s_branch .Lpw_ip1_d_pip

.Lpw_ip1_d_pip:
	s_waitcnt lgkmcnt(0)
	s_barrier
	s_setprio 1
	s_waitcnt lgkmcnt(0)
	v_mfma_f32_16x16x32_bf16 v[124:127], v[140:143], v[176:179], 0
	v_mfma_f32_16x16x32_bf16 v[120:123], v[152:155], v[176:179], 0
	v_mfma_f32_16x16x32_bf16 v[116:119], v[140:143], v[184:187], 0
	v_mfma_f32_16x16x32_bf16 v[108:111], v[152:155], v[184:187], 0
	v_mfma_f32_16x16x32_bf16 v[100:103], v[140:143], v[192:195], 0
	v_mfma_f32_16x16x32_bf16 v[92:95], v[152:155], v[192:195], 0
	v_mfma_f32_16x16x32_bf16 v[84:87], v[140:143], v[200:203], 0
	v_mfma_f32_16x16x32_bf16 v[76:79], v[152:155], v[200:203], 0
	v_mfma_f32_16x16x32_bf16 v[124:127], v[148:151], v[180:183], v[124:127]
	v_mfma_f32_16x16x32_bf16 v[120:123], v[156:159], v[180:183], v[120:123]
	v_mfma_f32_16x16x32_bf16 v[116:119], v[148:151], v[188:191], v[116:119]
	v_mfma_f32_16x16x32_bf16 v[108:111], v[156:159], v[188:191], v[108:111]
	v_mfma_f32_16x16x32_bf16 v[100:103], v[148:151], v[196:199], v[100:103]
	v_mfma_f32_16x16x32_bf16 v[92:95], v[156:159], v[196:199], v[92:95]
	v_mfma_f32_16x16x32_bf16 v[84:87], v[148:151], v[204:207], v[84:87]
	v_mfma_f32_16x16x32_bf16 v[76:79], v[156:159], v[204:207], v[76:79]
	s_setprio 0
	s_setprio 1
	v_mfma_f32_16x16x32_bf16 v[112:115], v[160:163], v[176:179], 0
	v_mfma_f32_16x16x32_bf16 v[104:107], v[168:171], v[176:179], 0
	v_mfma_f32_16x16x32_bf16 v[96:99], v[160:163], v[184:187], 0
	v_mfma_f32_16x16x32_bf16 v[88:91], v[168:171], v[184:187], 0
	v_mfma_f32_16x16x32_bf16 v[80:83], v[160:163], v[192:195], 0
	v_mfma_f32_16x16x32_bf16 v[72:75], v[168:171], v[192:195], 0
	v_mfma_f32_16x16x32_bf16 v[68:71], v[160:163], v[200:203], 0
	v_mfma_f32_16x16x32_bf16 v[64:67], v[168:171], v[200:203], 0
	v_mfma_f32_16x16x32_bf16 v[112:115], v[164:167], v[180:183], v[112:115]
	v_mfma_f32_16x16x32_bf16 v[104:107], v[172:175], v[180:183], v[104:107]
	v_mfma_f32_16x16x32_bf16 v[96:99], v[164:167], v[188:191], v[96:99]
	v_mfma_f32_16x16x32_bf16 v[88:91], v[172:175], v[188:191], v[88:91]
	v_mfma_f32_16x16x32_bf16 v[80:83], v[164:167], v[196:199], v[80:83]
	v_mfma_f32_16x16x32_bf16 v[72:75], v[172:175], v[196:199], v[72:75]
	v_mfma_f32_16x16x32_bf16 v[68:71], v[164:167], v[204:207], v[68:71]
	v_mfma_f32_16x16x32_bf16 v[64:67], v[172:175], v[204:207], v[64:67]
	s_setprio 0
	s_barrier
	s_add_i32 s49, s49, s23
	v_lshl_add_u64 v[208:209], s[16:17], 0, v[134:135]
	s_mov_b32 m0, s49
	ds_read_b128 v[176:179], v147 offset:16384
	ds_read_b128 v[180:183], v147 offset:17408
	ds_read_b128 v[184:187], v147 offset:18432
	ds_read_b128 v[188:191], v147 offset:19456
	ds_read_b128 v[192:195], v147 offset:20480
	ds_read_b128 v[196:199], v147 offset:21504
	ds_read_b128 v[200:203], v147 offset:22528
	ds_read_b128 v[204:207], v147 offset:23552
	global_load_lds_dwordx4 v[208:209], off
	s_add_i32 m0, s49, 0x2000
	s_add_u32 s50, s16, 0x80000
	v_lshl_add_u64 v[208:209], s[16:17], 0, v[130:131]
	s_addc_u32 s51, s17, 0
	s_add_i32 s49, s52, s23
	global_load_lds_dwordx4 v[208:209], off
	v_lshl_add_u64 v[208:209], s[50:51], 0, v[134:135]
	s_mov_b32 m0, s49
	v_lshl_add_u64 v[210:211], s[18:19], 0, v[132:133]
	global_load_lds_dwordx4 v[208:209], off
	v_lshl_add_u64 v[208:209], s[50:51], 0, v[130:131]
	s_add_i32 m0, s49, 0x2000
	s_nop 0
	global_load_lds_dwordx4 v[208:209], off
	v_lshl_add_u64 v[208:209], s[18:19], 0, v[128:129]
	s_mov_b32 m0, s24
	s_nop 0
	global_load_lds_dwordx4 v[208:209], off
	s_mov_b32 m0, s25
	s_nop 0
	global_load_lds_dwordx4 v[210:211], off
	s_cmp_eq_u32 s98, 0
	s_cbranch_scc1 .Lpw_ip2_n_pip
	s_waitcnt vmcnt(24)
	s_mov_b32 s98, 0
	s_branch .Lpw_ip2_d_pip

.Lpw_ip2_d_pip:
	s_waitcnt lgkmcnt(0)
	s_barrier
	s_setprio 1
	s_waitcnt lgkmcnt(0)
	v_mfma_f32_16x16x32_bf16 v[60:63], v[140:143], v[176:179], 0
	v_mfma_f32_16x16x32_bf16 v[56:59], v[152:155], v[176:179], 0
	v_mfma_f32_16x16x32_bf16 v[52:55], v[140:143], v[184:187], 0
	v_mfma_f32_16x16x32_bf16 v[44:47], v[152:155], v[184:187], 0
	v_mfma_f32_16x16x32_bf16 v[36:39], v[140:143], v[192:195], 0
	v_mfma_f32_16x16x32_bf16 v[28:31], v[152:155], v[192:195], 0
	v_mfma_f32_16x16x32_bf16 v[20:23], v[140:143], v[200:203], 0
	v_mfma_f32_16x16x32_bf16 v[12:15], v[152:155], v[200:203], 0
	v_mfma_f32_16x16x32_bf16 v[60:63], v[148:151], v[180:183], v[60:63]
	v_mfma_f32_16x16x32_bf16 v[56:59], v[156:159], v[180:183], v[56:59]
	v_mfma_f32_16x16x32_bf16 v[52:55], v[148:151], v[188:191], v[52:55]
	v_mfma_f32_16x16x32_bf16 v[44:47], v[156:159], v[188:191], v[44:47]
	v_mfma_f32_16x16x32_bf16 v[36:39], v[148:151], v[196:199], v[36:39]
	v_mfma_f32_16x16x32_bf16 v[28:31], v[156:159], v[196:199], v[28:31]
	v_mfma_f32_16x16x32_bf16 v[20:23], v[148:151], v[204:207], v[20:23]
	v_mfma_f32_16x16x32_bf16 v[12:15], v[156:159], v[204:207], v[12:15]
	s_setprio 0
	s_setprio 1
	v_mfma_f32_16x16x32_bf16 v[48:51], v[160:163], v[176:179], 0
	v_mfma_f32_16x16x32_bf16 v[40:43], v[168:171], v[176:179], 0
	v_mfma_f32_16x16x32_bf16 v[32:35], v[160:163], v[184:187], 0
	v_mfma_f32_16x16x32_bf16 v[24:27], v[168:171], v[184:187], 0
	v_mfma_f32_16x16x32_bf16 v[16:19], v[160:163], v[192:195], 0
	v_mfma_f32_16x16x32_bf16 v[8:11], v[168:171], v[192:195], 0
	v_mfma_f32_16x16x32_bf16 v[4:7], v[160:163], v[200:203], 0
	v_mfma_f32_16x16x32_bf16 v[0:3], v[168:171], v[200:203], 0
	v_mfma_f32_16x16x32_bf16 v[48:51], v[164:167], v[180:183], v[48:51]
	v_mfma_f32_16x16x32_bf16 v[40:43], v[172:175], v[180:183], v[40:43]
	v_mfma_f32_16x16x32_bf16 v[32:35], v[164:167], v[188:191], v[32:35]
	v_mfma_f32_16x16x32_bf16 v[24:27], v[172:175], v[188:191], v[24:27]
	v_mfma_f32_16x16x32_bf16 v[16:19], v[164:167], v[196:199], v[16:19]
	v_mfma_f32_16x16x32_bf16 v[8:11], v[172:175], v[196:199], v[8:11]
	v_mfma_f32_16x16x32_bf16 v[4:7], v[164:167], v[204:207], v[4:7]
	v_mfma_f32_16x16x32_bf16 v[0:3], v[172:175], v[204:207], v[0:3]
	s_setprio 0
	s_barrier
	s_add_i32 s49, 0, 0x18000
	s_add_i32 s50, 0, 0x1c000
	v_add_u32_e32 v156, s49, v145
	v_add_u32_e32 v172, s50, v145
	ds_read_b128 v[140:143], v156
	ds_read_b128 v[148:151], v156 offset:1024
	ds_read_b128 v[152:155], v156 offset:2048
	ds_read_b128 v[156:159], v156 offset:3072
	ds_read_b128 v[160:163], v172
	ds_read_b128 v[164:167], v172 offset:1024
	ds_read_b128 v[168:171], v172 offset:2048
	ds_read_b128 v[172:175], v172 offset:3072
	s_add_u32 s18, s18, 0x80000
	s_addc_u32 s19, s19, 0
	s_mov_b32 m0, s26
	v_lshl_add_u64 v[212:213], s[18:19], 0, v[128:129]
	ds_read_b128 v[176:179], v147 offset:32768
	ds_read_b128 v[180:183], v147 offset:33792
	ds_read_b128 v[184:187], v147 offset:34816
	ds_read_b128 v[188:191], v147 offset:35840
	ds_read_b128 v[192:195], v147 offset:36864
	ds_read_b128 v[196:199], v147 offset:37888
	ds_read_b128 v[200:203], v147 offset:38912
	ds_read_b128 v[204:207], v147 offset:39936
	global_load_lds_dwordx4 v[212:213], off
	v_lshl_add_u64 v[212:213], s[18:19], 0, v[132:133]
	s_mov_b32 m0, s27
	s_nop 0
	global_load_lds_dwordx4 v[212:213], off
	s_waitcnt vmcnt(8)
	s_waitcnt lgkmcnt(0)
	s_barrier
	s_setprio 1
	s_waitcnt lgkmcnt(0)
	v_mfma_f32_16x16x32_bf16 v[124:127], v[140:143], v[176:179], v[124:127]
	v_mfma_f32_16x16x32_bf16 v[120:123], v[152:155], v[176:179], v[120:123]
	v_mfma_f32_16x16x32_bf16 v[116:119], v[140:143], v[184:187], v[116:119]
	v_mfma_f32_16x16x32_bf16 v[108:111], v[152:155], v[184:187], v[108:111]
	v_mfma_f32_16x16x32_bf16 v[100:103], v[140:143], v[192:195], v[100:103]
	v_mfma_f32_16x16x32_bf16 v[92:95], v[152:155], v[192:195], v[92:95]
	v_mfma_f32_16x16x32_bf16 v[84:87], v[140:143], v[200:203], v[84:87]
	v_mfma_f32_16x16x32_bf16 v[76:79], v[152:155], v[200:203], v[76:79]
	v_mfma_f32_16x16x32_bf16 v[124:127], v[148:151], v[180:183], v[124:127]
	v_mfma_f32_16x16x32_bf16 v[120:123], v[156:159], v[180:183], v[120:123]
	v_mfma_f32_16x16x32_bf16 v[116:119], v[148:151], v[188:191], v[116:119]
	v_mfma_f32_16x16x32_bf16 v[108:111], v[156:159], v[188:191], v[108:111]
	v_mfma_f32_16x16x32_bf16 v[100:103], v[148:151], v[196:199], v[100:103]
	v_mfma_f32_16x16x32_bf16 v[92:95], v[156:159], v[196:199], v[92:95]
	v_mfma_f32_16x16x32_bf16 v[84:87], v[148:151], v[204:207], v[84:87]
	v_mfma_f32_16x16x32_bf16 v[76:79], v[156:159], v[204:207], v[76:79]
	s_setprio 0
	s_setprio 1
	v_mfma_f32_16x16x32_bf16 v[112:115], v[160:163], v[176:179], v[112:115]
	v_mfma_f32_16x16x32_bf16 v[104:107], v[168:171], v[176:179], v[104:107]
	v_mfma_f32_16x16x32_bf16 v[96:99], v[160:163], v[184:187], v[96:99]
	v_mfma_f32_16x16x32_bf16 v[88:91], v[168:171], v[184:187], v[88:91]
	v_mfma_f32_16x16x32_bf16 v[80:83], v[160:163], v[192:195], v[80:83]
	v_mfma_f32_16x16x32_bf16 v[72:75], v[168:171], v[192:195], v[72:75]
	v_mfma_f32_16x16x32_bf16 v[68:71], v[160:163], v[200:203], v[68:71]
	v_mfma_f32_16x16x32_bf16 v[64:67], v[168:171], v[200:203], v[64:67]
	v_mfma_f32_16x16x32_bf16 v[112:115], v[164:167], v[180:183], v[112:115]
	v_mfma_f32_16x16x32_bf16 v[104:107], v[172:175], v[180:183], v[104:107]
	v_mfma_f32_16x16x32_bf16 v[96:99], v[164:167], v[188:191], v[96:99]
	v_mfma_f32_16x16x32_bf16 v[88:91], v[172:175], v[188:191], v[88:91]
	v_mfma_f32_16x16x32_bf16 v[80:83], v[164:167], v[196:199], v[80:83]
	v_mfma_f32_16x16x32_bf16 v[72:75], v[172:175], v[196:199], v[72:75]
	v_mfma_f32_16x16x32_bf16 v[68:71], v[164:167], v[204:207], v[68:71]
	v_mfma_f32_16x16x32_bf16 v[64:67], v[172:175], v[204:207], v[64:67]
	s_setprio 0
	s_barrier
	s_add_u32 s18, s16, 0x4000
	s_addc_u32 s19, s17, 0
	s_add_i32 s49, s49, s23
	v_lshl_add_u64 v[212:213], s[18:19], 0, v[134:135]
	s_mov_b32 m0, s49
	ds_read_b128 v[176:179], v147 offset:49152
	ds_read_b128 v[180:183], v147 offset:50176
	ds_read_b128 v[184:187], v147 offset:51200
	ds_read_b128 v[188:191], v147 offset:52224
	ds_read_b128 v[192:195], v147 offset:53248
	ds_read_b128 v[196:199], v147 offset:54272
	ds_read_b128 v[200:203], v147 offset:55296
	ds_read_b128 v[204:207], v147 offset:56320
	global_load_lds_dwordx4 v[212:213], off
	s_add_i32 m0, s49, 0x2000
	s_add_u32 s16, s16, 0x84000
	v_lshl_add_u64 v[212:213], s[18:19], 0, v[130:131]
	s_addc_u32 s17, s17, 0
	s_add_i32 s18, s50, s23
	global_load_lds_dwordx4 v[212:213], off
	v_lshl_add_u64 v[212:213], s[16:17], 0, v[134:135]
	s_mov_b32 m0, s18
	v_lshl_add_u64 v[208:209], v[208:209], 0, s[34:35]
	global_load_lds_dwordx4 v[212:213], off
	v_lshl_add_u64 v[212:213], s[16:17], 0, v[130:131]
	s_add_i32 m0, s18, 0x2000
	s_nop 0
	global_load_lds_dwordx4 v[212:213], off
	s_mov_b32 m0, s28
	s_nop 0
	global_load_lds_dwordx4 v[208:209], off
	v_lshl_add_u64 v[208:209], v[210:211], 0, s[34:35]
	s_mov_b32 m0, s29
	s_nop 0
	global_load_lds_dwordx4 v[208:209], off
	s_waitcnt vmcnt(8)
	s_waitcnt lgkmcnt(0)
	s_barrier
	s_setprio 1
	s_waitcnt lgkmcnt(0)
	v_mfma_f32_16x16x32_bf16 v[60:63], v[140:143], v[176:179], v[60:63]
	v_mfma_f32_16x16x32_bf16 v[56:59], v[152:155], v[176:179], v[56:59]
	v_mfma_f32_16x16x32_bf16 v[52:55], v[140:143], v[184:187], v[52:55]
	v_mfma_f32_16x16x32_bf16 v[44:47], v[152:155], v[184:187], v[44:47]
	v_mfma_f32_16x16x32_bf16 v[36:39], v[140:143], v[192:195], v[36:39]
	v_mfma_f32_16x16x32_bf16 v[28:31], v[152:155], v[192:195], v[28:31]
	v_mfma_f32_16x16x32_bf16 v[20:23], v[140:143], v[200:203], v[20:23]
	v_mfma_f32_16x16x32_bf16 v[12:15], v[152:155], v[200:203], v[12:15]
	v_mfma_f32_16x16x32_bf16 v[60:63], v[148:151], v[180:183], v[60:63]
	v_mfma_f32_16x16x32_bf16 v[56:59], v[156:159], v[180:183], v[56:59]
	v_mfma_f32_16x16x32_bf16 v[52:55], v[148:151], v[188:191], v[52:55]
	v_mfma_f32_16x16x32_bf16 v[44:47], v[156:159], v[188:191], v[44:47]
	v_mfma_f32_16x16x32_bf16 v[36:39], v[148:151], v[196:199], v[36:39]
	v_mfma_f32_16x16x32_bf16 v[28:31], v[156:159], v[196:199], v[28:31]
	v_mfma_f32_16x16x32_bf16 v[20:23], v[148:151], v[204:207], v[20:23]
	v_mfma_f32_16x16x32_bf16 v[12:15], v[156:159], v[204:207], v[12:15]
	s_setprio 0
	s_setprio 1
	v_mfma_f32_16x16x32_bf16 v[48:51], v[160:163], v[176:179], v[48:51]
	v_mfma_f32_16x16x32_bf16 v[40:43], v[168:171], v[176:179], v[40:43]
	v_mfma_f32_16x16x32_bf16 v[32:35], v[160:163], v[184:187], v[32:35]
	v_mfma_f32_16x16x32_bf16 v[24:27], v[168:171], v[184:187], v[24:27]
	v_mfma_f32_16x16x32_bf16 v[16:19], v[160:163], v[192:195], v[16:19]
	v_mfma_f32_16x16x32_bf16 v[8:11], v[168:171], v[192:195], v[8:11]
	v_mfma_f32_16x16x32_bf16 v[4:7], v[160:163], v[200:203], v[4:7]
	v_mfma_f32_16x16x32_bf16 v[0:3], v[168:171], v[200:203], v[0:3]
	v_mfma_f32_16x16x32_bf16 v[48:51], v[164:167], v[180:183], v[48:51]
	v_mfma_f32_16x16x32_bf16 v[40:43], v[172:175], v[180:183], v[40:43]
	v_mfma_f32_16x16x32_bf16 v[32:35], v[164:167], v[188:191], v[32:35]
	v_mfma_f32_16x16x32_bf16 v[24:27], v[172:175], v[188:191], v[24:27]
	v_mfma_f32_16x16x32_bf16 v[16:19], v[164:167], v[196:199], v[16:19]
	v_mfma_f32_16x16x32_bf16 v[8:11], v[172:175], v[196:199], v[8:11]
	v_mfma_f32_16x16x32_bf16 v[4:7], v[164:167], v[204:207], v[4:7]
	v_mfma_f32_16x16x32_bf16 v[0:3], v[172:175], v[204:207], v[0:3]
	s_setprio 0
	s_barrier
	s_add_i32 s48, s48, 2
	s_add_u32 s46, s46, 0x8000
	s_addc_u32 s47, s47, 0
	s_add_u32 s14, s14, 0x100
	s_addc_u32 s15, s15, 0
	s_cmp_gt_u32 s48, 29
	s_cbranch_scc0 .LBB0_550
	s_branch .Lpz_ip_exit
